# previous + same SGPR-base DMA conversion in the P4/P8 (tile-blocked A) loops: no 64-bit VALU address adds left there
# baseline (speedup 1.0000x reference)
.LBB0_519:
	s_add_i32 s39, s56, 0xfffe8000
	s_and_b32 s38, s36, 0x100
	s_and_b32 s39, s39, 0x3e0000
	s_or_b32 s38, s38, s39
	s_add_u32 s57, s34, s38
	s_addc_u32 s59, s35, 0
	s_add_u32 s38, s36, 0x100
	s_addc_u32 s39, s37, 0
	s_add_i32 s41, s56, 0xffff8000
	s_and_b32 s40, s38, 0x100
	s_and_b32 s41, s41, 0x7e0000
	s_or_b32 s40, s41, s40
	s_add_u32 s40, s34, s40
	s_addc_u32 s41, s35, 0
	s_add_u32 s58, s53, s36
	s_addc_u32 s37, s54, s37
	s_add_i32 s42, s36, 0x180
	s_and_b32 s42, s42, 0x180
	s_and_b32 s43, s56, 0x7e0000
	s_or_b32 s42, s43, s42
	s_add_u32 s60, s34, s42
	s_addc_u32 s61, s35, 0
	s_cmpk_eq_i32 s36, 0x3f00
	s_cselect_b32 s43, s1, s41
	s_cselect_b32 s42, s21, s40
	s_cselect_b32 s41, s23, s37
	s_cselect_b32 s40, s22, s58
	s_cselect_b32 s37, s52, s61
	s_cselect_b32 s36, s31, s60
	s_add_i32 s60, 0, 0x10000
	v_add_u32_e32 v1, s60, v199
	ds_read_b128 v[130:133], v1
	ds_read_b128 v[134:137], v1 offset:1024
	ds_read_b128 v[138:141], v1 offset:2048
	ds_read_b128 v[142:145], v1 offset:3072
	ds_read_b128 v[146:149], v201
	ds_read_b128 v[150:153], v201 offset:1024
	ds_read_b128 v[154:157], v201 offset:2048
	ds_read_b128 v[158:161], v201 offset:3072
	s_add_u32 s58, s57, 0x10080
	s_addc_u32 s59, s59, 0
	s_add_i32 m0, s3, 0xc000
	ds_read_b128 v[162:165], v202
	ds_read_b128 v[166:169], v202 offset:1024
	ds_read_b128 v[170:173], v202 offset:2048
	ds_read_b128 v[174:177], v202 offset:3072
	ds_read_b128 v[186:189], v202 offset:4096
	ds_read_b128 v[190:193], v202 offset:5120
	ds_read_b128 v[194:197], v202 offset:6144
	ds_read_b128 v[204:207], v202 offset:7168
	global_load_lds_dwordx4 v178, s[58:59]
	s_add_i32 m0, s3, 0xe000
	s_nop 0
	global_load_lds_dwordx4 v182, s[58:59]
	s_waitcnt vmcnt(8)
	s_waitcnt lgkmcnt(0)
	s_barrier
	s_waitcnt lgkmcnt(0)
	v_mfma_f32_16x16x32_bf16 v[126:129], v[130:133], v[162:165], v[126:129]
	v_mfma_f32_16x16x32_bf16 v[126:129], v[134:137], v[166:169], v[126:129]
	v_mfma_f32_16x16x32_bf16 v[122:125], v[142:145], v[166:169], v[122:125]
	v_mfma_f32_16x16x32_bf16 v[122:125], v[138:141], v[162:165], v[122:125]
	v_mfma_f32_16x16x32_bf16 v[106:109], v[138:141], v[170:173], v[106:109]
	v_mfma_f32_16x16x32_bf16 v[106:109], v[142:145], v[174:177], v[106:109]
	v_mfma_f32_16x16x32_bf16 v[110:113], v[134:137], v[174:177], v[110:113]
	v_mfma_f32_16x16x32_bf16 v[110:113], v[130:133], v[170:173], v[110:113]
	v_mfma_f32_16x16x32_bf16 v[94:97], v[130:133], v[186:189], v[94:97]
	v_mfma_f32_16x16x32_bf16 v[94:97], v[134:137], v[190:193], v[94:97]
	v_mfma_f32_16x16x32_bf16 v[90:93], v[142:145], v[190:193], v[90:93]
	v_mfma_f32_16x16x32_bf16 v[90:93], v[138:141], v[186:189], v[90:93]
	v_mfma_f32_16x16x32_bf16 v[74:77], v[138:141], v[194:197], v[74:77]
	v_mfma_f32_16x16x32_bf16 v[74:77], v[142:145], v[204:207], v[74:77]
	v_mfma_f32_16x16x32_bf16 v[78:81], v[134:137], v[204:207], v[78:81]
	v_mfma_f32_16x16x32_bf16 v[78:81], v[130:133], v[194:197], v[78:81]
	v_mfma_f32_16x16x32_bf16 v[118:121], v[146:149], v[162:165], v[118:121]
	v_mfma_f32_16x16x32_bf16 v[118:121], v[150:153], v[166:169], v[118:121]
	v_mfma_f32_16x16x32_bf16 v[114:117], v[158:161], v[166:169], v[114:117]
	v_mfma_f32_16x16x32_bf16 v[114:117], v[154:157], v[162:165], v[114:117]
	v_mfma_f32_16x16x32_bf16 v[98:101], v[154:157], v[170:173], v[98:101]
	v_mfma_f32_16x16x32_bf16 v[98:101], v[158:161], v[174:177], v[98:101]
	v_mfma_f32_16x16x32_bf16 v[102:105], v[150:153], v[174:177], v[102:105]
	v_mfma_f32_16x16x32_bf16 v[102:105], v[146:149], v[170:173], v[102:105]
	v_mfma_f32_16x16x32_bf16 v[86:89], v[146:149], v[186:189], v[86:89]
	v_mfma_f32_16x16x32_bf16 v[86:89], v[150:153], v[190:193], v[86:89]
	v_mfma_f32_16x16x32_bf16 v[82:85], v[158:161], v[190:193], v[82:85]
	v_mfma_f32_16x16x32_bf16 v[82:85], v[154:157], v[186:189], v[82:85]
	v_mfma_f32_16x16x32_bf16 v[66:69], v[154:157], v[194:197], v[66:69]
	v_mfma_f32_16x16x32_bf16 v[66:69], v[158:161], v[204:207], v[66:69]
	v_mfma_f32_16x16x32_bf16 v[70:73], v[150:153], v[204:207], v[70:73]
	v_mfma_f32_16x16x32_bf16 v[70:73], v[146:149], v[194:197], v[70:73]
	s_barrier
	s_add_i32 s57, s60, s2
	s_mov_b32 m0, s57
	ds_read_b128 v[162:165], v202 offset:16384
	ds_read_b128 v[166:169], v202 offset:17408
	ds_read_b128 v[170:173], v202 offset:18432
	ds_read_b128 v[174:177], v202 offset:19456
	ds_read_b128 v[186:189], v202 offset:20480
	ds_read_b128 v[190:193], v202 offset:21504
	ds_read_b128 v[194:197], v202 offset:22528
	ds_read_b128 v[204:207], v202 offset:23552
	global_load_lds_dwordx4 v180, s[40:41]
	s_add_i32 m0, s57, 0x2000
	s_add_u32 s58, s40, 0x208000
	s_addc_u32 s59, s41, 0
	s_add_i32 s57, s49, s2
	global_load_lds_dwordx4 v184, s[40:41]
	s_mov_b32 m0, s57
	s_nop 0
	global_load_lds_dwordx4 v180, s[58:59]
	s_add_i32 m0, s57, 0x2000
	s_nop 0
	global_load_lds_dwordx4 v184, s[58:59]
	s_mov_b32 m0, s3
	s_nop 0
	global_load_lds_dwordx4 v178, s[42:43]
	s_mov_b32 m0, s33
	s_nop 0
	global_load_lds_dwordx4 v182, s[42:43]
	s_waitcnt vmcnt(8)
	s_waitcnt lgkmcnt(0)
	s_barrier
	s_waitcnt lgkmcnt(0)
	v_mfma_f32_16x16x32_bf16 v[62:65], v[130:133], v[162:165], v[62:65]
	v_mfma_f32_16x16x32_bf16 v[62:65], v[134:137], v[166:169], v[62:65]
	v_mfma_f32_16x16x32_bf16 v[58:61], v[142:145], v[166:169], v[58:61]
	v_mfma_f32_16x16x32_bf16 v[58:61], v[138:141], v[162:165], v[58:61]
	v_mfma_f32_16x16x32_bf16 v[42:45], v[138:141], v[170:173], v[42:45]
	v_mfma_f32_16x16x32_bf16 v[42:45], v[142:145], v[174:177], v[42:45]
	v_mfma_f32_16x16x32_bf16 v[46:49], v[134:137], v[174:177], v[46:49]
	v_mfma_f32_16x16x32_bf16 v[46:49], v[130:133], v[170:173], v[46:49]
	v_mfma_f32_16x16x32_bf16 v[30:33], v[130:133], v[186:189], v[30:33]
	v_mfma_f32_16x16x32_bf16 v[30:33], v[134:137], v[190:193], v[30:33]
	v_mfma_f32_16x16x32_bf16 v[26:29], v[142:145], v[190:193], v[26:29]
	v_mfma_f32_16x16x32_bf16 v[26:29], v[138:141], v[186:189], v[26:29]
	v_mfma_f32_16x16x32_bf16 v[10:13], v[138:141], v[194:197], v[10:13]
	v_mfma_f32_16x16x32_bf16 v[10:13], v[142:145], v[204:207], v[10:13]
	v_mfma_f32_16x16x32_bf16 v[14:17], v[134:137], v[204:207], v[14:17]
	v_mfma_f32_16x16x32_bf16 v[14:17], v[130:133], v[194:197], v[14:17]
	v_mfma_f32_16x16x32_bf16 v[54:57], v[146:149], v[162:165], v[54:57]
	v_mfma_f32_16x16x32_bf16 v[54:57], v[150:153], v[166:169], v[54:57]
	v_mfma_f32_16x16x32_bf16 v[50:53], v[158:161], v[166:169], v[50:53]
	v_mfma_f32_16x16x32_bf16 v[50:53], v[154:157], v[162:165], v[50:53]
	v_mfma_f32_16x16x32_bf16 v[34:37], v[154:157], v[170:173], v[34:37]
	v_mfma_f32_16x16x32_bf16 v[34:37], v[158:161], v[174:177], v[34:37]
	v_mfma_f32_16x16x32_bf16 v[38:41], v[150:153], v[174:177], v[38:41]
	v_mfma_f32_16x16x32_bf16 v[38:41], v[146:149], v[170:173], v[38:41]
	v_mfma_f32_16x16x32_bf16 v[22:25], v[146:149], v[186:189], v[22:25]
	v_mfma_f32_16x16x32_bf16 v[22:25], v[150:153], v[190:193], v[22:25]
	v_mfma_f32_16x16x32_bf16 v[18:21], v[158:161], v[190:193], v[18:21]
	v_mfma_f32_16x16x32_bf16 v[18:21], v[154:157], v[186:189], v[18:21]
	v_mfma_f32_16x16x32_bf16 v[2:5], v[154:157], v[194:197], v[2:5]
	v_mfma_f32_16x16x32_bf16 v[2:5], v[158:161], v[204:207], v[2:5]
	v_mfma_f32_16x16x32_bf16 v[6:9], v[150:153], v[204:207], v[6:9]
	v_mfma_f32_16x16x32_bf16 v[6:9], v[146:149], v[194:197], v[6:9]
	s_barrier
	s_add_i32 s57, 0, 0x18000
	v_add_u32_e32 v1, s57, v199
	s_add_i32 s58, 0, 0x1c000
	ds_read_b128 v[130:133], v1
	ds_read_b128 v[134:137], v1 offset:1024
	ds_read_b128 v[138:141], v1 offset:2048
	ds_read_b128 v[142:145], v1 offset:3072
	v_add_u32_e32 v1, s58, v199
	ds_read_b128 v[146:149], v1
	ds_read_b128 v[150:153], v1 offset:1024
	ds_read_b128 v[154:157], v1 offset:2048
	ds_read_b128 v[158:161], v1 offset:3072
	s_add_u32 s42, s42, 0x10000
	s_addc_u32 s43, s43, 0
	s_mov_b32 m0, s44
	ds_read_b128 v[162:165], v202 offset:32768
	ds_read_b128 v[166:169], v202 offset:33792
	ds_read_b128 v[170:173], v202 offset:34816
	ds_read_b128 v[174:177], v202 offset:35840
	ds_read_b128 v[186:189], v202 offset:36864
	ds_read_b128 v[190:193], v202 offset:37888
	ds_read_b128 v[194:197], v202 offset:38912
	ds_read_b128 v[204:207], v202 offset:39936
	global_load_lds_dwordx4 v178, s[42:43]
	s_mov_b32 m0, s45
	s_nop 0
	global_load_lds_dwordx4 v182, s[42:43]
	s_waitcnt vmcnt(8)
	s_waitcnt lgkmcnt(0)
	s_barrier
	s_waitcnt lgkmcnt(0)
	v_mfma_f32_16x16x32_bf16 v[126:129], v[130:133], v[162:165], v[126:129]
	v_mfma_f32_16x16x32_bf16 v[126:129], v[134:137], v[166:169], v[126:129]
	v_mfma_f32_16x16x32_bf16 v[122:125], v[142:145], v[166:169], v[122:125]
	v_mfma_f32_16x16x32_bf16 v[122:125], v[138:141], v[162:165], v[122:125]
	v_mfma_f32_16x16x32_bf16 v[106:109], v[138:141], v[170:173], v[106:109]
	v_mfma_f32_16x16x32_bf16 v[106:109], v[142:145], v[174:177], v[106:109]
	v_mfma_f32_16x16x32_bf16 v[110:113], v[134:137], v[174:177], v[110:113]
	v_mfma_f32_16x16x32_bf16 v[110:113], v[130:133], v[170:173], v[110:113]
	v_mfma_f32_16x16x32_bf16 v[94:97], v[130:133], v[186:189], v[94:97]
	v_mfma_f32_16x16x32_bf16 v[94:97], v[134:137], v[190:193], v[94:97]
	v_mfma_f32_16x16x32_bf16 v[90:93], v[142:145], v[190:193], v[90:93]
	v_mfma_f32_16x16x32_bf16 v[90:93], v[138:141], v[186:189], v[90:93]
	v_mfma_f32_16x16x32_bf16 v[74:77], v[138:141], v[194:197], v[74:77]
	v_mfma_f32_16x16x32_bf16 v[74:77], v[142:145], v[204:207], v[74:77]
	v_mfma_f32_16x16x32_bf16 v[78:81], v[134:137], v[204:207], v[78:81]
	v_mfma_f32_16x16x32_bf16 v[78:81], v[130:133], v[194:197], v[78:81]
	v_mfma_f32_16x16x32_bf16 v[118:121], v[146:149], v[162:165], v[118:121]
	v_mfma_f32_16x16x32_bf16 v[118:121], v[150:153], v[166:169], v[118:121]
	v_mfma_f32_16x16x32_bf16 v[114:117], v[158:161], v[166:169], v[114:117]
	v_mfma_f32_16x16x32_bf16 v[114:117], v[154:157], v[162:165], v[114:117]
	v_mfma_f32_16x16x32_bf16 v[98:101], v[154:157], v[170:173], v[98:101]
	v_mfma_f32_16x16x32_bf16 v[98:101], v[158:161], v[174:177], v[98:101]
	v_mfma_f32_16x16x32_bf16 v[102:105], v[150:153], v[174:177], v[102:105]
	v_mfma_f32_16x16x32_bf16 v[102:105], v[146:149], v[170:173], v[102:105]
	v_mfma_f32_16x16x32_bf16 v[86:89], v[146:149], v[186:189], v[86:89]
	v_mfma_f32_16x16x32_bf16 v[86:89], v[150:153], v[190:193], v[86:89]
	v_mfma_f32_16x16x32_bf16 v[82:85], v[158:161], v[190:193], v[82:85]
	v_mfma_f32_16x16x32_bf16 v[82:85], v[154:157], v[186:189], v[82:85]
	v_mfma_f32_16x16x32_bf16 v[66:69], v[154:157], v[194:197], v[66:69]
	v_mfma_f32_16x16x32_bf16 v[66:69], v[158:161], v[204:207], v[66:69]
	v_mfma_f32_16x16x32_bf16 v[70:73], v[150:153], v[204:207], v[70:73]
	v_mfma_f32_16x16x32_bf16 v[70:73], v[146:149], v[194:197], v[70:73]
	s_barrier
	s_add_i32 s42, s57, s2
	s_add_u32 s40, s40, 0x80
	s_addc_u32 s41, s41, 0
	s_mov_b32 m0, s42
	ds_read_b128 v[162:165], v202 offset:49152
	ds_read_b128 v[166:169], v202 offset:50176
	ds_read_b128 v[170:173], v202 offset:51200
	ds_read_b128 v[174:177], v202 offset:52224
	ds_read_b128 v[186:189], v202 offset:53248
	ds_read_b128 v[190:193], v202 offset:54272
	ds_read_b128 v[194:197], v202 offset:55296
	ds_read_b128 v[204:207], v202 offset:56320
	global_load_lds_dwordx4 v180, s[40:41]
	s_add_i32 m0, s42, 0x2000
	s_add_i32 s42, s58, s2
	global_load_lds_dwordx4 v184, s[40:41]
	s_add_u32 s40, s40, 0x208000
	s_addc_u32 s41, s41, 0
	s_mov_b32 m0, s42
	s_nop 0
	global_load_lds_dwordx4 v180, s[40:41]
	s_add_i32 m0, s42, 0x2000
	s_nop 0
	global_load_lds_dwordx4 v184, s[40:41]
	s_mov_b32 m0, s47
	s_nop 0
	global_load_lds_dwordx4 v178, s[36:37]
	s_mov_b32 m0, s48
	s_nop 0
	global_load_lds_dwordx4 v182, s[36:37]
	s_waitcnt vmcnt(8)
	s_waitcnt lgkmcnt(0)
	s_barrier
	s_waitcnt lgkmcnt(0)
	v_mfma_f32_16x16x32_bf16 v[62:65], v[130:133], v[162:165], v[62:65]
	v_mfma_f32_16x16x32_bf16 v[62:65], v[134:137], v[166:169], v[62:65]
	v_mfma_f32_16x16x32_bf16 v[58:61], v[142:145], v[166:169], v[58:61]
	v_mfma_f32_16x16x32_bf16 v[58:61], v[138:141], v[162:165], v[58:61]
	v_mfma_f32_16x16x32_bf16 v[42:45], v[138:141], v[170:173], v[42:45]
	v_mfma_f32_16x16x32_bf16 v[42:45], v[142:145], v[174:177], v[42:45]
	v_mfma_f32_16x16x32_bf16 v[46:49], v[134:137], v[174:177], v[46:49]
	v_mfma_f32_16x16x32_bf16 v[46:49], v[130:133], v[170:173], v[46:49]
	v_mfma_f32_16x16x32_bf16 v[30:33], v[130:133], v[186:189], v[30:33]
	v_mfma_f32_16x16x32_bf16 v[30:33], v[134:137], v[190:193], v[30:33]
	v_mfma_f32_16x16x32_bf16 v[26:29], v[142:145], v[190:193], v[26:29]
	v_mfma_f32_16x16x32_bf16 v[26:29], v[138:141], v[186:189], v[26:29]
	v_mfma_f32_16x16x32_bf16 v[10:13], v[138:141], v[194:197], v[10:13]
	v_mfma_f32_16x16x32_bf16 v[10:13], v[142:145], v[204:207], v[10:13]
	v_mfma_f32_16x16x32_bf16 v[14:17], v[134:137], v[204:207], v[14:17]
	v_mfma_f32_16x16x32_bf16 v[14:17], v[130:133], v[194:197], v[14:17]
	v_mfma_f32_16x16x32_bf16 v[54:57], v[146:149], v[162:165], v[54:57]
	v_mfma_f32_16x16x32_bf16 v[54:57], v[150:153], v[166:169], v[54:57]
	v_mfma_f32_16x16x32_bf16 v[50:53], v[158:161], v[166:169], v[50:53]
	v_mfma_f32_16x16x32_bf16 v[50:53], v[154:157], v[162:165], v[50:53]
	v_mfma_f32_16x16x32_bf16 v[34:37], v[154:157], v[170:173], v[34:37]
	v_mfma_f32_16x16x32_bf16 v[34:37], v[158:161], v[174:177], v[34:37]
	v_mfma_f32_16x16x32_bf16 v[38:41], v[150:153], v[174:177], v[38:41]
	v_mfma_f32_16x16x32_bf16 v[38:41], v[146:149], v[170:173], v[38:41]
	v_mfma_f32_16x16x32_bf16 v[22:25], v[146:149], v[186:189], v[22:25]
	v_mfma_f32_16x16x32_bf16 v[22:25], v[150:153], v[190:193], v[22:25]
	v_mfma_f32_16x16x32_bf16 v[18:21], v[158:161], v[190:193], v[18:21]
	v_mfma_f32_16x16x32_bf16 v[18:21], v[154:157], v[186:189], v[18:21]
	v_mfma_f32_16x16x32_bf16 v[2:5], v[154:157], v[194:197], v[2:5]
	v_mfma_f32_16x16x32_bf16 v[2:5], v[158:161], v[204:207], v[2:5]
	v_mfma_f32_16x16x32_bf16 v[6:9], v[150:153], v[204:207], v[6:9]
	v_mfma_f32_16x16x32_bf16 v[6:9], v[146:149], v[194:197], v[6:9]
	s_barrier
	s_add_i32 s55, s55, 2
	s_add_i32 s56, s56, 0x10000
	s_cmpk_gt_u32 s55, 0x7d
	s_mov_b64 s[36:37], s[38:39]
	s_cbranch_scc0 .LBB0_519
	s_and_b64 vcc, exec, s[18:19]
	s_cbranch_vccz .LBB0_522
	s_barrier

.LBB0_844:
	s_add_i32 s35, s52, 0xfffe8000
	s_and_b32 s34, s30, 0x100
	s_and_b32 s35, s35, 0x3e0000
	s_or_b32 s34, s34, s35
	s_add_u32 s53, s28, s34
	s_addc_u32 s55, s29, 0
	s_add_u32 s34, s30, 0x100
	s_addc_u32 s35, s31, 0
	s_add_i32 s37, s52, 0xffff8000
	s_and_b32 s36, s34, 0x100
	s_and_b32 s37, s37, 0x7e0000
	s_or_b32 s36, s37, s36
	s_add_u32 s36, s28, s36
	s_addc_u32 s37, s29, 0
	s_add_u32 s54, s49, s30
	s_addc_u32 s31, s50, s31
	s_add_i32 s38, s30, 0x180
	s_and_b32 s38, s38, 0x180
	s_and_b32 s39, s52, 0x7e0000
	s_or_b32 s38, s39, s38
	s_add_u32 s56, s28, s38
	s_addc_u32 s57, s29, 0
	s_cmpk_eq_i32 s30, 0x3f00
	s_cselect_b32 s39, s1, s37
	s_cselect_b32 s38, s21, s36
	s_cselect_b32 s37, s23, s31
	s_cselect_b32 s36, s22, s54
	s_cselect_b32 s31, s48, s57
	s_cselect_b32 s30, s27, s56
	s_add_i32 s56, 0, 0x10000
	v_add_u32_e32 v124, s56, v211
	ds_read_b128 v[104:107], v124
	ds_read_b128 v[108:111], v124 offset:1024
	ds_read_b128 v[120:123], v124 offset:2048
	ds_read_b128 v[124:127], v124 offset:3072
	ds_read_b128 v[144:147], v214
	ds_read_b128 v[148:151], v214 offset:1024
	ds_read_b128 v[152:155], v214 offset:2048
	ds_read_b128 v[156:159], v214 offset:3072
	s_add_u32 s54, s53, 0x10080
	s_addc_u32 s55, s55, 0
	s_add_i32 m0, s3, 0xc000
	ds_read_b128 v[160:163], v215
	ds_read_b128 v[164:167], v215 offset:1024
	ds_read_b128 v[168:171], v215 offset:2048
	ds_read_b128 v[172:175], v215 offset:3072
	ds_read_b128 v[176:179], v215 offset:4096
	ds_read_b128 v[180:183], v215 offset:5120
	ds_read_b128 v[192:195], v215 offset:6144
	ds_read_b128 v[196:199], v215 offset:7168
	global_load_lds_dwordx4 v184, s[54:55]
	s_add_i32 m0, s3, 0xe000
	s_nop 0
	global_load_lds_dwordx4 v188, s[54:55]
	s_waitcnt vmcnt(8)
	s_waitcnt lgkmcnt(0)
	s_barrier
	s_waitcnt lgkmcnt(0)
	v_mfma_f32_16x16x32_bf16 v[140:143], v[104:107], v[160:163], v[140:143]
	v_mfma_f32_16x16x32_bf16 v[140:143], v[108:111], v[164:167], v[140:143]
	v_mfma_f32_16x16x32_bf16 v[136:139], v[124:127], v[164:167], v[136:139]
	v_mfma_f32_16x16x32_bf16 v[136:139], v[120:123], v[160:163], v[136:139]
	v_mfma_f32_16x16x32_bf16 v[112:115], v[120:123], v[168:171], v[112:115]
	v_mfma_f32_16x16x32_bf16 v[112:115], v[124:127], v[172:175], v[112:115]
	v_mfma_f32_16x16x32_bf16 v[116:119], v[108:111], v[172:175], v[116:119]
	v_mfma_f32_16x16x32_bf16 v[116:119], v[104:107], v[168:171], v[116:119]
	v_mfma_f32_16x16x32_bf16 v[92:95], v[104:107], v[176:179], v[92:95]
	v_mfma_f32_16x16x32_bf16 v[92:95], v[108:111], v[180:183], v[92:95]
	v_mfma_f32_16x16x32_bf16 v[88:91], v[124:127], v[180:183], v[88:91]
	v_mfma_f32_16x16x32_bf16 v[88:91], v[120:123], v[176:179], v[88:91]
	v_mfma_f32_16x16x32_bf16 v[72:75], v[120:123], v[192:195], v[72:75]
	v_mfma_f32_16x16x32_bf16 v[72:75], v[124:127], v[196:199], v[72:75]
	v_mfma_f32_16x16x32_bf16 v[76:79], v[108:111], v[196:199], v[76:79]
	v_mfma_f32_16x16x32_bf16 v[76:79], v[104:107], v[192:195], v[76:79]
	v_mfma_f32_16x16x32_bf16 v[132:135], v[144:147], v[160:163], v[132:135]
	v_mfma_f32_16x16x32_bf16 v[132:135], v[148:151], v[164:167], v[132:135]
	v_mfma_f32_16x16x32_bf16 v[128:131], v[156:159], v[164:167], v[128:131]
	v_mfma_f32_16x16x32_bf16 v[128:131], v[152:155], v[160:163], v[128:131]
	v_mfma_f32_16x16x32_bf16 v[96:99], v[152:155], v[168:171], v[96:99]
	v_mfma_f32_16x16x32_bf16 v[96:99], v[156:159], v[172:175], v[96:99]
	v_mfma_f32_16x16x32_bf16 v[100:103], v[148:151], v[172:175], v[100:103]
	v_mfma_f32_16x16x32_bf16 v[100:103], v[144:147], v[168:171], v[100:103]
	v_mfma_f32_16x16x32_bf16 v[84:87], v[144:147], v[176:179], v[84:87]
	v_mfma_f32_16x16x32_bf16 v[84:87], v[148:151], v[180:183], v[84:87]
	v_mfma_f32_16x16x32_bf16 v[80:83], v[156:159], v[180:183], v[80:83]
	v_mfma_f32_16x16x32_bf16 v[80:83], v[152:155], v[176:179], v[80:83]
	v_mfma_f32_16x16x32_bf16 v[64:67], v[152:155], v[192:195], v[64:67]
	v_mfma_f32_16x16x32_bf16 v[64:67], v[156:159], v[196:199], v[64:67]
	v_mfma_f32_16x16x32_bf16 v[68:71], v[148:151], v[196:199], v[68:71]
	v_mfma_f32_16x16x32_bf16 v[68:71], v[144:147], v[192:195], v[68:71]
	s_barrier
	s_add_i32 s53, s56, s2
	s_mov_b32 m0, s53
	ds_read_b128 v[160:163], v215 offset:16384
	ds_read_b128 v[164:167], v215 offset:17408
	ds_read_b128 v[168:171], v215 offset:18432
	ds_read_b128 v[172:175], v215 offset:19456
	ds_read_b128 v[176:179], v215 offset:20480
	ds_read_b128 v[180:183], v215 offset:21504
	ds_read_b128 v[192:195], v215 offset:22528
	ds_read_b128 v[196:199], v215 offset:23552
	global_load_lds_dwordx4 v186, s[36:37]
	s_add_i32 m0, s53, 0x2000
	s_add_u32 s54, s36, 0x208000
	s_addc_u32 s55, s37, 0
	s_add_i32 s53, s45, s2
	global_load_lds_dwordx4 v190, s[36:37]
	s_mov_b32 m0, s53
	s_nop 0
	global_load_lds_dwordx4 v186, s[54:55]
	s_add_i32 m0, s53, 0x2000
	s_nop 0
	global_load_lds_dwordx4 v190, s[54:55]
	s_mov_b32 m0, s3
	s_nop 0
	global_load_lds_dwordx4 v184, s[38:39]
	s_mov_b32 m0, s33
	s_nop 0
	global_load_lds_dwordx4 v188, s[38:39]
	s_waitcnt vmcnt(8)
	s_waitcnt lgkmcnt(0)
	s_barrier
	s_waitcnt lgkmcnt(0)
	v_mfma_f32_16x16x32_bf16 v[60:63], v[104:107], v[160:163], v[60:63]
	v_mfma_f32_16x16x32_bf16 v[60:63], v[108:111], v[164:167], v[60:63]
	v_mfma_f32_16x16x32_bf16 v[56:59], v[124:127], v[164:167], v[56:59]
	v_mfma_f32_16x16x32_bf16 v[56:59], v[120:123], v[160:163], v[56:59]
	v_mfma_f32_16x16x32_bf16 v[40:43], v[120:123], v[168:171], v[40:43]
	v_mfma_f32_16x16x32_bf16 v[40:43], v[124:127], v[172:175], v[40:43]
	v_mfma_f32_16x16x32_bf16 v[44:47], v[108:111], v[172:175], v[44:47]
	v_mfma_f32_16x16x32_bf16 v[44:47], v[104:107], v[168:171], v[44:47]
	v_mfma_f32_16x16x32_bf16 v[28:31], v[104:107], v[176:179], v[28:31]
	v_mfma_f32_16x16x32_bf16 v[28:31], v[108:111], v[180:183], v[28:31]
	v_mfma_f32_16x16x32_bf16 v[24:27], v[124:127], v[180:183], v[24:27]
	v_mfma_f32_16x16x32_bf16 v[24:27], v[120:123], v[176:179], v[24:27]
	v_mfma_f32_16x16x32_bf16 v[8:11], v[120:123], v[192:195], v[8:11]
	v_mfma_f32_16x16x32_bf16 v[8:11], v[124:127], v[196:199], v[8:11]
	v_mfma_f32_16x16x32_bf16 v[12:15], v[108:111], v[196:199], v[12:15]
	v_mfma_f32_16x16x32_bf16 v[12:15], v[104:107], v[192:195], v[12:15]
	v_mfma_f32_16x16x32_bf16 v[52:55], v[144:147], v[160:163], v[52:55]
	v_mfma_f32_16x16x32_bf16 v[52:55], v[148:151], v[164:167], v[52:55]
	v_mfma_f32_16x16x32_bf16 v[48:51], v[156:159], v[164:167], v[48:51]
	v_mfma_f32_16x16x32_bf16 v[48:51], v[152:155], v[160:163], v[48:51]
	v_mfma_f32_16x16x32_bf16 v[32:35], v[152:155], v[168:171], v[32:35]
	v_mfma_f32_16x16x32_bf16 v[32:35], v[156:159], v[172:175], v[32:35]
	v_mfma_f32_16x16x32_bf16 v[36:39], v[148:151], v[172:175], v[36:39]
	v_mfma_f32_16x16x32_bf16 v[36:39], v[144:147], v[168:171], v[36:39]
	v_mfma_f32_16x16x32_bf16 v[20:23], v[144:147], v[176:179], v[20:23]
	v_mfma_f32_16x16x32_bf16 v[20:23], v[148:151], v[180:183], v[20:23]
	v_mfma_f32_16x16x32_bf16 v[16:19], v[156:159], v[180:183], v[16:19]
	v_mfma_f32_16x16x32_bf16 v[16:19], v[152:155], v[176:179], v[16:19]
	v_mfma_f32_16x16x32_bf16 v[0:3], v[152:155], v[192:195], v[0:3]
	v_mfma_f32_16x16x32_bf16 v[0:3], v[156:159], v[196:199], v[0:3]
	v_mfma_f32_16x16x32_bf16 v[4:7], v[148:151], v[196:199], v[4:7]
	v_mfma_f32_16x16x32_bf16 v[4:7], v[144:147], v[192:195], v[4:7]
	s_barrier
	s_add_i32 s53, 0, 0x18000
	s_add_i32 s54, 0, 0x1c000
	v_add_u32_e32 v124, s53, v211
	v_add_u32_e32 v156, s54, v211
	ds_read_b128 v[104:107], v124
	ds_read_b128 v[108:111], v124 offset:1024
	ds_read_b128 v[120:123], v124 offset:2048
	ds_read_b128 v[124:127], v124 offset:3072
	ds_read_b128 v[144:147], v156
	ds_read_b128 v[148:151], v156 offset:1024
	ds_read_b128 v[152:155], v156 offset:2048
	ds_read_b128 v[156:159], v156 offset:3072
	s_add_u32 s38, s38, 0x10000
	s_addc_u32 s39, s39, 0
	s_mov_b32 m0, s40
	ds_read_b128 v[160:163], v215 offset:32768
	ds_read_b128 v[164:167], v215 offset:33792
	ds_read_b128 v[168:171], v215 offset:34816
	ds_read_b128 v[172:175], v215 offset:35840
	ds_read_b128 v[176:179], v215 offset:36864
	ds_read_b128 v[180:183], v215 offset:37888
	ds_read_b128 v[192:195], v215 offset:38912
	ds_read_b128 v[196:199], v215 offset:39936
	global_load_lds_dwordx4 v184, s[38:39]
	s_mov_b32 m0, s41
	s_nop 0
	global_load_lds_dwordx4 v188, s[38:39]
	s_waitcnt vmcnt(8)
	s_waitcnt lgkmcnt(0)
	s_barrier
	s_waitcnt lgkmcnt(0)
	v_mfma_f32_16x16x32_bf16 v[140:143], v[104:107], v[160:163], v[140:143]
	v_mfma_f32_16x16x32_bf16 v[140:143], v[108:111], v[164:167], v[140:143]
	v_mfma_f32_16x16x32_bf16 v[136:139], v[124:127], v[164:167], v[136:139]
	v_mfma_f32_16x16x32_bf16 v[136:139], v[120:123], v[160:163], v[136:139]
	v_mfma_f32_16x16x32_bf16 v[112:115], v[120:123], v[168:171], v[112:115]
	v_mfma_f32_16x16x32_bf16 v[112:115], v[124:127], v[172:175], v[112:115]
	v_mfma_f32_16x16x32_bf16 v[116:119], v[108:111], v[172:175], v[116:119]
	v_mfma_f32_16x16x32_bf16 v[116:119], v[104:107], v[168:171], v[116:119]
	v_mfma_f32_16x16x32_bf16 v[92:95], v[104:107], v[176:179], v[92:95]
	v_mfma_f32_16x16x32_bf16 v[92:95], v[108:111], v[180:183], v[92:95]
	v_mfma_f32_16x16x32_bf16 v[88:91], v[124:127], v[180:183], v[88:91]
	v_mfma_f32_16x16x32_bf16 v[88:91], v[120:123], v[176:179], v[88:91]
	v_mfma_f32_16x16x32_bf16 v[72:75], v[120:123], v[192:195], v[72:75]
	v_mfma_f32_16x16x32_bf16 v[72:75], v[124:127], v[196:199], v[72:75]
	v_mfma_f32_16x16x32_bf16 v[76:79], v[108:111], v[196:199], v[76:79]
	v_mfma_f32_16x16x32_bf16 v[76:79], v[104:107], v[192:195], v[76:79]
	v_mfma_f32_16x16x32_bf16 v[132:135], v[144:147], v[160:163], v[132:135]
	v_mfma_f32_16x16x32_bf16 v[132:135], v[148:151], v[164:167], v[132:135]
	v_mfma_f32_16x16x32_bf16 v[128:131], v[156:159], v[164:167], v[128:131]
	v_mfma_f32_16x16x32_bf16 v[128:131], v[152:155], v[160:163], v[128:131]
	v_mfma_f32_16x16x32_bf16 v[96:99], v[152:155], v[168:171], v[96:99]
	v_mfma_f32_16x16x32_bf16 v[96:99], v[156:159], v[172:175], v[96:99]
	v_mfma_f32_16x16x32_bf16 v[100:103], v[148:151], v[172:175], v[100:103]
	v_mfma_f32_16x16x32_bf16 v[100:103], v[144:147], v[168:171], v[100:103]
	v_mfma_f32_16x16x32_bf16 v[84:87], v[144:147], v[176:179], v[84:87]
	v_mfma_f32_16x16x32_bf16 v[84:87], v[148:151], v[180:183], v[84:87]
	v_mfma_f32_16x16x32_bf16 v[80:83], v[156:159], v[180:183], v[80:83]
	v_mfma_f32_16x16x32_bf16 v[80:83], v[152:155], v[176:179], v[80:83]
	v_mfma_f32_16x16x32_bf16 v[64:67], v[152:155], v[192:195], v[64:67]
	v_mfma_f32_16x16x32_bf16 v[64:67], v[156:159], v[196:199], v[64:67]
	v_mfma_f32_16x16x32_bf16 v[68:71], v[148:151], v[196:199], v[68:71]
	v_mfma_f32_16x16x32_bf16 v[68:71], v[144:147], v[192:195], v[68:71]
	s_barrier
	s_add_i32 s38, s53, s2
	s_add_u32 s36, s36, 0x80
	s_addc_u32 s37, s37, 0
	s_mov_b32 m0, s38
	ds_read_b128 v[160:163], v215 offset:49152
	ds_read_b128 v[164:167], v215 offset:50176
	ds_read_b128 v[168:171], v215 offset:51200
	ds_read_b128 v[172:175], v215 offset:52224
	ds_read_b128 v[176:179], v215 offset:53248
	ds_read_b128 v[180:183], v215 offset:54272
	ds_read_b128 v[192:195], v215 offset:55296
	ds_read_b128 v[196:199], v215 offset:56320
	global_load_lds_dwordx4 v186, s[36:37]
	s_add_i32 m0, s38, 0x2000
	s_add_i32 s38, s54, s2
	global_load_lds_dwordx4 v190, s[36:37]
	s_add_u32 s36, s36, 0x208000
	s_addc_u32 s37, s37, 0
	s_mov_b32 m0, s38
	s_nop 0
	global_load_lds_dwordx4 v186, s[36:37]
	s_add_i32 m0, s38, 0x2000
	s_nop 0
	global_load_lds_dwordx4 v190, s[36:37]
	s_mov_b32 m0, s43
	s_nop 0
	global_load_lds_dwordx4 v184, s[30:31]
	s_mov_b32 m0, s44
	s_nop 0
	global_load_lds_dwordx4 v188, s[30:31]
	s_waitcnt vmcnt(8)
	s_waitcnt lgkmcnt(0)
	s_barrier
	s_waitcnt lgkmcnt(0)
	v_mfma_f32_16x16x32_bf16 v[60:63], v[104:107], v[160:163], v[60:63]
	v_mfma_f32_16x16x32_bf16 v[60:63], v[108:111], v[164:167], v[60:63]
	v_mfma_f32_16x16x32_bf16 v[56:59], v[124:127], v[164:167], v[56:59]
	v_mfma_f32_16x16x32_bf16 v[56:59], v[120:123], v[160:163], v[56:59]
	v_mfma_f32_16x16x32_bf16 v[40:43], v[120:123], v[168:171], v[40:43]
	v_mfma_f32_16x16x32_bf16 v[40:43], v[124:127], v[172:175], v[40:43]
	v_mfma_f32_16x16x32_bf16 v[44:47], v[108:111], v[172:175], v[44:47]
	v_mfma_f32_16x16x32_bf16 v[44:47], v[104:107], v[168:171], v[44:47]
	v_mfma_f32_16x16x32_bf16 v[28:31], v[104:107], v[176:179], v[28:31]
	v_mfma_f32_16x16x32_bf16 v[28:31], v[108:111], v[180:183], v[28:31]
	v_mfma_f32_16x16x32_bf16 v[24:27], v[124:127], v[180:183], v[24:27]
	v_mfma_f32_16x16x32_bf16 v[24:27], v[120:123], v[176:179], v[24:27]
	v_mfma_f32_16x16x32_bf16 v[8:11], v[120:123], v[192:195], v[8:11]
	v_mfma_f32_16x16x32_bf16 v[8:11], v[124:127], v[196:199], v[8:11]
	v_mfma_f32_16x16x32_bf16 v[12:15], v[108:111], v[196:199], v[12:15]
	v_mfma_f32_16x16x32_bf16 v[12:15], v[104:107], v[192:195], v[12:15]
	v_mfma_f32_16x16x32_bf16 v[52:55], v[144:147], v[160:163], v[52:55]
	v_mfma_f32_16x16x32_bf16 v[52:55], v[148:151], v[164:167], v[52:55]
	v_mfma_f32_16x16x32_bf16 v[48:51], v[156:159], v[164:167], v[48:51]
	v_mfma_f32_16x16x32_bf16 v[48:51], v[152:155], v[160:163], v[48:51]
	v_mfma_f32_16x16x32_bf16 v[32:35], v[152:155], v[168:171], v[32:35]
	v_mfma_f32_16x16x32_bf16 v[32:35], v[156:159], v[172:175], v[32:35]
	v_mfma_f32_16x16x32_bf16 v[36:39], v[148:151], v[172:175], v[36:39]
	v_mfma_f32_16x16x32_bf16 v[36:39], v[144:147], v[168:171], v[36:39]
	v_mfma_f32_16x16x32_bf16 v[20:23], v[144:147], v[176:179], v[20:23]
	v_mfma_f32_16x16x32_bf16 v[20:23], v[148:151], v[180:183], v[20:23]
	v_mfma_f32_16x16x32_bf16 v[16:19], v[156:159], v[180:183], v[16:19]
	v_mfma_f32_16x16x32_bf16 v[16:19], v[152:155], v[176:179], v[16:19]
	v_mfma_f32_16x16x32_bf16 v[0:3], v[152:155], v[192:195], v[0:3]
	v_mfma_f32_16x16x32_bf16 v[0:3], v[156:159], v[196:199], v[0:3]
	v_mfma_f32_16x16x32_bf16 v[4:7], v[148:151], v[196:199], v[4:7]
	v_mfma_f32_16x16x32_bf16 v[4:7], v[144:147], v[192:195], v[4:7]
	s_barrier
	s_add_i32 s51, s51, 2
	s_add_i32 s52, s52, 0x10000
	s_cmpk_gt_u32 s51, 0x7d
	s_mov_b64 s[30:31], s[34:35]
	s_cbranch_scc0 .LBB0_844
	s_and_b64 vcc, exec, s[18:19]
	s_cbranch_vccz .LBB0_847
	s_barrier
